# P0: x->bf16 loop and rotary-table loop walk waves/threads in reverse order so the workgroups that got a 5th weight-transpose item no longer also get the extra row/table iterations
# speedup vs baseline: 1.0093x; 1.0003x over previous
; __global__ void __launch_bounds__(512, 2) fwd_megakernel(Ptrs P) {
;     ...
;         for (int row0 = gw; row0 < MP; row0 += 2 * NGW) {
;             f32x4 v[2][4]; bool okr[2]; int rws[2];
; #pragma unroll
;             for (int q = 0; q < 2; ++q) { const int row = row0 + q * NGW; rws[q] = row; okr[q] = row < MREAL;
;                 const f32x4* xr = (const f32x4*)xin_row(P, okr[q] ? row : 0) + lane;
; #pragma unroll
;                 for (int j = 0; j < 4; ++j) v[q][j] = xr[64 * j]; }
.LBB0_408:
	v_readlane_b32 s1, v254, 48
	s_nop 0
	s_sub_i32 s0, s1, s0
	s_add_i32 s0, s0, -1
	v_readlane_b32 s8, v254, 9
	v_readlane_b32 s9, v254, 10
	s_add_u32 s2, s8, 0x4a00000
	s_addc_u32 s3, s9, 0
	v_readlane_b32 s10, v254, 11
	v_readlane_b32 s11, v254, 12
	v_writelane_b32 v254, s2, 49
	s_cmp_gt_i32 s0, 0x80ff
	v_mbcnt_lo_u32_b32 v234, -1, 0
	v_writelane_b32 v254, s3, 50
	v_cmp_eq_u32_e64 s[2:3], 0, v210
	s_cbranch_scc1 .LBB0_424
	v_readlane_b32 s6, v254, 49
	v_mov_b32_e32 v35, 0
	v_lshlrev_b32_e32 v34, 3, v210
	v_readlane_b32 s7, v254, 50
	v_readlane_b32 s8, v254, 9
	v_readlane_b32 s10, v254, 11
	v_lshl_add_u64 v[36:37], s[6:7], 0, v[34:35]
	v_mbcnt_hi_u32_b32 v34, -1, v234
	v_and_b32_e32 v2, 64, v34
	s_mov_b32 s6, 0
	s_lshl_b32 s14, s10, 4
	v_lshlrev_b32_e32 v1, 4, v210
	v_add_u32_e32 v40, 64, v2
	v_xor_b32_e32 v41, 1, v34
	v_xor_b32_e32 v42, 2, v34
	v_xor_b32_e32 v43, 4, v34
	v_xor_b32_e32 v44, 8, v34
	v_xor_b32_e32 v45, 16, v34
	v_xor_b32_e32 v46, 32, v34
	v_readlane_b32 s9, v254, 10
	v_readlane_b32 s11, v254, 12
	s_branch .LBB0_412

; __global__ void __launch_bounds__(512, 2) fwd_megakernel(Ptrs P) {
;     ...
;         const int gt = bx * 512 + tid, NGT = G * 512;
;         for (int i = gt; i < 2049 * 136; i += NGT) { const int p = i / 136, f = i % 136; const float pos = (p < 2048) ? (float)p : 16384.0f;
;             double inv; float* dst;
;             if (f < 8) { inv = my_exp(-(double)f / 8.0 * 13.122363377404328); dst = ROPE + ((size_t)p * 8 + f) * 2; }
;             else { const int q = f - 8; inv = my_exp(-(double)q / 127.0 * 9.210340371976184); dst = RROT + ((size_t)p * 128 + q) * 2; }
;             const float ang = pos * (float)inv; double s, c; my_sincos((double)ang, s, c); dst[0] = (float)c; dst[1] = (float)s; }
.LBB0_424:
	v_readlane_b32 s0, v254, 9
	v_readlane_b32 s1, v254, 10
	s_waitcnt lgkmcnt(0)
	s_add_u32 s26, s0, 0x200000
	s_addc_u32 s27, s1, 0
	s_add_u32 s20, s0, 0x240000
	v_readlane_b32 s0, v254, 0
	s_addc_u32 s21, s1, 0
	v_readlane_b32 s2, v254, 11
	v_lshl_add_u32 v1, s0, 9, v208
	s_lshl_b32 s6, s2, 9
	s_add_i32 s6, s6, -1
	v_sub_u32_e32 v1, s6, v1
	s_mov_b32 s0, 0x44088
	v_cmp_gt_i32_e32 vcc, s0, v1
	v_readlane_b32 s3, v254, 12
	s_and_saveexec_b64 s[0:1], vcc
	s_cbranch_execz .LBB0_433
	v_readlane_b32 s8, v254, 9
	v_readlane_b32 s9, v254, 10
	v_readlane_b32 s10, v254, 11
	v_readlane_b32 s11, v254, 12
	s_lshl_b32 s33, s10, 9
	s_mov_b32 s6, 0
	s_mov_b32 s8, 0xbbb55516
	s_mov_b32 s10, 0xfefa39ef
	s_mov_b32 s14, 0
	s_mov_b32 s16, 0
	s_mov_b32 s18, 0
	s_mov_b32 s28, 0
	s_mov_b32 s30, 0
	s_mov_b32 s38, 0
	s_mov_b32 s40, 0
	s_mov_b32 s42, 0
	s_mov_b32 s44, 0
	s_mov_b32 s46, 0
	s_mov_b32 s48, 0
	s_mov_b32 s50, 0
	s_mov_b32 s52, 0
	s_mov_b32 s54, 0
	s_mov_b32 s56, 0x69a05c01
	s_mov_b32 s58, 0x54442d18
	s_mov_b32 s62, 0x33145c07
	s_mov_b64 s[2:3], 0
	s_mov_b32 s7, 0xc05fc000
	s_mov_b32 s9, 0x40226bb1
	s_mov_b32 s11, 0x3fe62e42
	s_mov_b32 s13, 0xbfe62e42
	s_mov_b32 s15, 0x3fb00000
	s_mov_b32 s17, 0x402e0000
	s_mov_b32 s19, 0x402c0000
	s_mov_b32 s29, 0x402a0000
	s_mov_b32 s31, 0x40280000
	s_mov_b32 s39, 0x40260000
	s_mov_b32 s41, 0x40240000
	s_mov_b32 s43, 0x40220000
	s_mov_b32 s45, 0x3fc00000
	s_mov_b32 s47, 0x401c0000
	s_mov_b32 s49, 0x40180000
	s_mov_b32 s51, 0x40140000
	s_mov_b32 s53, 0x3fd00000
	s_mov_b32 s55, 0x40080000
	s_movk_i32 s66, 0xffe0
	s_waitcnt vmcnt(0)
	v_mov_b32_e32 v2, 0
	s_mov_b32 s57, 0x402a3ea6
	s_mov_b32 s59, 0x401921fb
	s_mov_b32 s61, 0xc01921fb
	s_mov_b32 s63, 0xbcb1a626
	v_mov_b32_e32 v16, 0x3ff00000
	v_mov_b32_e32 v17, 0x46800000
